# final stack plus spatial-phase bias/gain loads hoisted ahead of the MFMA block (four exposed L2 round trips per item removed)
# baseline (speedup 1.0000x reference)
.LBB0_209:
	s_or_b64 exec, exec, s[18:19]
	s_and_b32 s18, s39, 7
	s_lshl_b32 s78, s18, 7
	v_lshl_add_u64 v[0:1], s[78:79], 0, v[72:73]
	v_lshlrev_b64 v[0:1], 9, v[0:1]
	v_lshl_add_u64 v[4:5], v[80:81], 0, v[0:1]
	s_waitcnt lgkmcnt(0)
	s_barrier
	global_load_dwordx4 v[0:3], v[4:5], off offset:16
	s_nop 0
	global_load_dwordx4 v[4:7], v[4:5], off
	ds_read_b128 v[8:11], v113
	ds_read_b128 v[12:15], v113 offset:16
	v_readlane_b32 s2, v246, 27
	v_readlane_b32 s3, v246, 28
	v_readlane_b32 vcc_lo, v246, 15
	v_readlane_b32 vcc_hi, v246, 16
	s_movk_i32 s19, 0x2080
	s_add_i32 s39, s39, s76
	s_waitcnt vmcnt(0) lgkmcnt(0)
	v_mul_f32_e32 v4, v4, v8
	v_cndmask_b32_e64 v8, v4, 0, s[2:3]
	v_readlane_b32 s2, v246, 25
	v_mul_f32_e32 v5, v5, v9
	v_readlane_b32 s3, v246, 26
	s_nop 1
	v_cndmask_b32_e64 v9, 0, v5, s[2:3]
	v_pk_mul_f32 v[4:5], v[6:7], v[10:11]
	v_pk_mul_f32 v[6:7], v[2:3], v[14:15]
	v_pk_mul_f32 v[2:3], v[0:1], v[12:13]
	v_readlane_b32 s2, v246, 11
	v_cvt_pk_bf16_f32 v1, v4, v5
	v_readlane_b32 s3, v246, 12
	v_cvt_pk_bf16_f32 v2, v2, v3
	v_cndmask_b32_e64 v3, v2, 0, vcc
	v_cndmask_b32_e64 v4, v1, 0, s[2:3]
	v_readlane_b32 s2, v246, 23
	v_readlane_b32 vcc_lo, v246, 13
	v_lshrrev_b32_e32 v1, 16, v1
	v_readlane_b32 s3, v246, 24
	v_lshrrev_b32_e32 v2, 16, v2
	v_readlane_b32 vcc_hi, v246, 14
	v_cndmask_b32_e64 v1, v1, 0, s[2:3]
	s_mov_b32 s2, 0x5040100
	v_cndmask_b32_e64 v2, v2, 0, vcc
	v_readlane_b32 vcc_lo, v246, 19
	v_perm_b32 v2, v2, v3, s2
	v_cvt_pk_bf16_f32 v3, v6, v7
	v_readlane_b32 vcc_hi, v246, 20
	v_perm_b32 v1, v1, v4, s2
	v_cvt_pk_bf16_f32 v0, v8, v9
	v_cndmask_b32_e64 v4, v3, 0, vcc
	v_readlane_b32 vcc_lo, v246, 17
	v_lshrrev_b32_e32 v3, 16, v3
	v_readlane_b32 vcc_hi, v246, 18
	s_nop 1
	v_cndmask_b32_e64 v3, v3, 0, vcc
	v_perm_b32 v3, v3, v4, s2
	ds_write_b128 v69, v[0:3] offset:1024
	v_lshl_add_u64 v[0:1], s[78:79], 0, v[74:75]
	v_lshlrev_b64 v[0:1], 9, v[0:1]
	v_lshl_add_u64 v[4:5], v[80:81], 0, v[0:1]
	global_load_dwordx4 v[0:3], v[4:5], off offset:16
	s_nop 0
	global_load_dwordx4 v[4:7], v[4:5], off
	ds_read_b128 v[8:11], v113
	ds_read_b128 v[12:15], v113 offset:16
	v_readlane_b32 vcc_lo, v246, 21
	v_readlane_b32 vcc_hi, v246, 22
	s_waitcnt vmcnt(0) lgkmcnt(1)
	v_mul_f32_e32 v4, v4, v8
	v_mul_f32_e32 v5, v5, v9
	v_cndmask_b32_e64 v8, v4, 0, vcc
	v_cndmask_b32_e64 v9, 0, v5, s[22:23]
	v_pk_mul_f32 v[4:5], v[6:7], v[10:11]
	s_waitcnt lgkmcnt(0)
	v_pk_mul_f32 v[6:7], v[2:3], v[14:15]
	v_pk_mul_f32 v[2:3], v[0:1], v[12:13]
	v_cvt_pk_bf16_f32 v1, v4, v5
	v_cvt_pk_bf16_f32 v2, v2, v3
	v_cndmask_b32_e64 v3, v2, 0, s[30:31]
	v_lshrrev_b32_e32 v2, 16, v2
	v_cndmask_b32_e64 v4, v1, 0, s[26:27]
	v_lshrrev_b32_e32 v1, 16, v1
	v_cndmask_b32_e64 v2, v2, 0, s[28:29]
	v_cndmask_b32_e64 v1, v1, 0, s[24:25]
	v_perm_b32 v2, v2, v3, s2
	v_cvt_pk_bf16_f32 v3, v6, v7
	v_perm_b32 v1, v1, v4, s2
	v_cndmask_b32_e64 v4, v3, 0, s[36:37]
	v_lshrrev_b32_e32 v3, 16, v3
	v_cndmask_b32_e64 v3, v3, 0, s[34:35]
	v_cvt_pk_bf16_f32 v0, v8, v9
	v_perm_b32 v3, v3, v4, s2
	ds_write_b128 v114, v[0:3] offset:1024
	v_lshl_add_u64 v[0:1], s[78:79], 0, v[76:77]
	v_lshlrev_b64 v[0:1], 9, v[0:1]
	v_lshl_add_u64 v[4:5], v[80:81], 0, v[0:1]
	global_load_dwordx4 v[0:3], v[4:5], off offset:16
	s_nop 0
	global_load_dwordx4 v[4:7], v[4:5], off
	ds_read_b128 v[8:11], v113
	ds_read_b128 v[12:15], v113 offset:16
	s_lshl_b32 vcc_lo, s18, 9
	s_mov_b32 vcc_hi, s79
	s_waitcnt vmcnt(0) lgkmcnt(1)
	v_mul_f32_e32 v4, v4, v8
	v_mul_f32_e32 v5, v5, v9
	v_cndmask_b32_e64 v8, v4, 0, s[72:73]
	v_cndmask_b32_e64 v9, 0, v5, s[0:1]
	v_pk_mul_f32 v[4:5], v[6:7], v[10:11]
	s_waitcnt lgkmcnt(0)
	v_pk_mul_f32 v[6:7], v[2:3], v[14:15]
	v_pk_mul_f32 v[2:3], v[0:1], v[12:13]
	v_cvt_pk_bf16_f32 v1, v4, v5
	v_cvt_pk_bf16_f32 v2, v2, v3
	v_cndmask_b32_e64 v3, v2, 0, s[10:11]
	v_lshrrev_b32_e32 v2, 16, v2
	v_cndmask_b32_e64 v4, v1, 0, s[6:7]
	v_lshrrev_b32_e32 v1, 16, v1
	v_cndmask_b32_e64 v2, v2, 0, s[8:9]
	v_cndmask_b32_e64 v1, v1, 0, s[4:5]
	v_perm_b32 v2, v2, v3, s2
	v_cvt_pk_bf16_f32 v3, v6, v7
	v_perm_b32 v1, v1, v4, s2
	v_cndmask_b32_e64 v4, v3, 0, s[52:53]
	v_lshrrev_b32_e32 v3, 16, v3
	v_cndmask_b32_e64 v3, v3, 0, s[50:51]
	v_cvt_pk_bf16_f32 v0, v8, v9
	v_perm_b32 v3, v3, v4, s2
	ds_write_b128 v115, v[0:3] offset:1024
	v_lshl_add_u64 v[0:1], s[78:79], 0, v[78:79]
	v_lshlrev_b64 v[0:1], 9, v[0:1]
	v_lshl_add_u64 v[4:5], v[80:81], 0, v[0:1]
	global_load_dwordx4 v[0:3], v[4:5], off offset:16
	s_nop 0
	global_load_dwordx4 v[4:7], v[4:5], off
	ds_read_b128 v[8:11], v113
	ds_read_b128 v[12:15], v113 offset:16
	s_waitcnt vmcnt(0) lgkmcnt(1)
	v_mul_f32_e32 v4, v4, v8
	v_mul_f32_e32 v5, v5, v9
	v_cndmask_b32_e64 v8, v4, 0, s[54:55]
	v_cndmask_b32_e64 v9, 0, v5, s[56:57]
	v_pk_mul_f32 v[4:5], v[6:7], v[10:11]
	s_waitcnt lgkmcnt(0)
	v_pk_mul_f32 v[6:7], v[2:3], v[14:15]
	v_pk_mul_f32 v[2:3], v[0:1], v[12:13]
	v_cvt_pk_bf16_f32 v1, v4, v5
	v_cvt_pk_bf16_f32 v2, v2, v3
	v_cndmask_b32_e64 v3, v2, 0, s[64:65]
	v_lshrrev_b32_e32 v2, 16, v2
	v_cndmask_b32_e64 v4, v1, 0, s[60:61]
	v_lshrrev_b32_e32 v1, 16, v1
	v_cndmask_b32_e64 v2, v2, 0, s[62:63]
	v_cndmask_b32_e64 v1, v1, 0, s[20:21]
	v_perm_b32 v2, v2, v3, s2
	v_cvt_pk_bf16_f32 v3, v6, v7
	v_perm_b32 v1, v1, v4, s2
	v_cndmask_b32_e64 v4, v3, 0, s[68:69]
	v_lshrrev_b32_e32 v3, 16, v3
	v_cndmask_b32_e64 v3, v3, 0, s[66:67]
	v_cvt_pk_bf16_f32 v0, v8, v9
	v_perm_b32 v3, v3, v4, s2
	ds_write_b128 v116, v[0:3] offset:1024
	v_or_b32_e32 v2, s16, v66
	v_mov_b64_e32 v[0:1], s[12:13]
	v_mad_u64_u32 v[0:1], s[2:3], v2, s19, v[0:1]
	v_mad_i32_i24 v1, s17, v206, v1
	v_lshl_add_u64 v[0:1], v[0:1], 0, vcc
	s_mov_b64 s[2:3], 0x1000
	v_lshl_add_u64 v[0:1], v[0:1], 0, s[2:3]
	v_lshl_add_u64 v[10:11], v[82:83], 1, v[0:1]
	global_load_dwordx4 v[10:13], v[10:11], off
	v_lshl_add_u64 v[14:15], v[84:85], 1, v[0:1]
	s_waitcnt vmcnt(0)
	ds_write_b16 v117, v10 offset:35840
	ds_write_b16_d16_hi v117, v10 offset:36112
	ds_write_b16 v117, v11 offset:36384
	ds_write_b16_d16_hi v117, v11 offset:36656
	ds_write_b16 v117, v12 offset:36928
	ds_write_b16_d16_hi v117, v12 offset:37200
	ds_write_b16 v117, v13 offset:37472
	ds_write_b16_d16_hi v117, v13 offset:37744
	global_load_dwordx4 v[10:13], v[14:15], off
	v_lshl_add_u64 v[16:17], v[86:87], 1, v[0:1]
	s_waitcnt vmcnt(0)
	ds_write_b16 v118, v10 offset:35840
	ds_write_b16_d16_hi v118, v10 offset:36112
	ds_write_b16 v118, v11 offset:36384
	ds_write_b16_d16_hi v118, v11 offset:36656
	ds_write_b16 v118, v12 offset:36928
	ds_write_b16_d16_hi v118, v12 offset:37200
	ds_write_b16 v118, v13 offset:37472
	ds_write_b16_d16_hi v118, v13 offset:37744
	global_load_dwordx4 v[10:13], v[16:17], off
	v_lshl_add_u64 v[8:9], v[88:89], 1, v[0:1]
	s_waitcnt vmcnt(0)
	ds_write_b16 v119, v10 offset:35840
	ds_write_b16_d16_hi v119, v10 offset:36112
	ds_write_b16 v119, v11 offset:36384
	ds_write_b16_d16_hi v119, v11 offset:36656
	ds_write_b16 v119, v12 offset:36928
	ds_write_b16_d16_hi v119, v12 offset:37200
	ds_write_b16 v119, v13 offset:37472
	ds_write_b16_d16_hi v119, v13 offset:37744
	global_load_dwordx4 v[8:11], v[8:9], off
	v_lshl_add_u64 v[6:7], v[90:91], 1, v[0:1]
	s_waitcnt vmcnt(0)
	ds_write_b16 v120, v8 offset:35840
	ds_write_b16_d16_hi v120, v8 offset:36112
	ds_write_b16 v120, v9 offset:36384
	ds_write_b16_d16_hi v120, v9 offset:36656
	ds_write_b16 v120, v10 offset:36928
	ds_write_b16_d16_hi v120, v10 offset:37200
	ds_write_b16 v120, v11 offset:37472
	ds_write_b16_d16_hi v120, v11 offset:37744
	global_load_dwordx4 v[6:9], v[6:7], off
	v_lshl_add_u64 v[4:5], v[92:93], 1, v[0:1]
	s_waitcnt vmcnt(0)
	ds_write_b16 v121, v6 offset:35840
	ds_write_b16_d16_hi v121, v6 offset:36112
	ds_write_b16 v121, v7 offset:36384
	ds_write_b16_d16_hi v121, v7 offset:36656
	ds_write_b16 v121, v8 offset:36928
	ds_write_b16_d16_hi v121, v8 offset:37200
	ds_write_b16 v121, v9 offset:37472
	ds_write_b16_d16_hi v121, v9 offset:37744
	global_load_dwordx4 v[4:7], v[4:5], off
	v_lshl_add_u64 v[2:3], v[94:95], 1, v[0:1]
	s_waitcnt vmcnt(0)
	ds_write_b16 v122, v4 offset:35840
	ds_write_b16_d16_hi v122, v4 offset:36112
	ds_write_b16 v122, v5 offset:36384
	ds_write_b16_d16_hi v122, v5 offset:36656
	ds_write_b16 v122, v6 offset:36928
	ds_write_b16_d16_hi v122, v6 offset:37200
	ds_write_b16 v122, v7 offset:37472
	ds_write_b16_d16_hi v122, v7 offset:37744
	global_load_dwordx4 v[2:5], v[2:3], off
	v_lshl_add_u64 v[0:1], v[96:97], 1, v[0:1]
	s_waitcnt vmcnt(0)
	ds_write_b16 v123, v2 offset:35840
	ds_write_b16_d16_hi v123, v2 offset:36112
	ds_write_b16 v123, v3 offset:36384
	ds_write_b16_d16_hi v123, v3 offset:36656
	ds_write_b16 v123, v4 offset:36928
	ds_write_b16_d16_hi v123, v4 offset:37200
	ds_write_b16 v123, v5 offset:37472
	ds_write_b16_d16_hi v123, v5 offset:37744
	global_load_dwordx4 v[0:3], v[0:1], off
	s_waitcnt vmcnt(0)
	ds_write_b16 v124, v0 offset:35840
	ds_write_b16_d16_hi v124, v0 offset:36112
	ds_write_b16 v124, v1 offset:36384
	ds_write_b16_d16_hi v124, v1 offset:36656
	ds_write_b16 v124, v2 offset:36928
	ds_write_b16_d16_hi v124, v2 offset:37200
	ds_write_b16 v124, v3 offset:37472
	ds_write_b16_d16_hi v124, v3 offset:37744
	s_waitcnt lgkmcnt(0)
	s_barrier
	v_or_b32_e32 v230, s78, v67
	v_lshlrev_b32_e32 v230, 2, v230
	v_mov_b32_e32 v234, s78
	v_lshlrev_b32_e32 v234, 3, v234
	v_mov_b32_e32 v235, 0
	v_lshl_add_u64 v[232:233], v[106:107], 0, v[234:235]
	global_load_dword v226, v230, s[14:15]
	global_load_dwordx4 v[210:213], v[232:233], off
	global_load_dwordx4 v[214:217], v[232:233], off offset:32
	global_load_dwordx4 v[218:221], v[232:233], off offset:64
	global_load_dwordx4 v[222:225], v[232:233], off offset:96
	global_load_dword v227, v230, s[14:15] offset:128
	global_load_dword v228, v230, s[14:15] offset:256
	global_load_dword v229, v230, s[14:15] offset:384
	ds_read_b128 v[0:3], v68 offset:35840
	ds_read_b128 v[108:111], v68 offset:35872
	ds_read_b128 v[4:7], v125 offset:1024
	ds_read_b128 v[134:137], v125 offset:1056
	s_waitcnt lgkmcnt(1)
	v_mfma_f32_32x32x16_bf16 v[48:63], v[0:3], v[4:7], 0
	ds_read_b128 v[4:7], v126 offset:1024
	ds_read_b128 v[138:141], v126 offset:1056
	s_waitcnt lgkmcnt(1)
	v_mfma_f32_32x32x16_bf16 v[32:47], v[0:3], v[4:7], 0
	ds_read_b128 v[4:7], v125 offset:18432
	s_waitcnt lgkmcnt(0)
	v_mfma_f32_32x32x16_bf16 v[16:31], v[0:3], v[4:7], 0
	ds_read_b128 v[4:7], v127 offset:1024
	ds_read_b128 v[142:145], v127 offset:1056
	s_waitcnt lgkmcnt(1)
	v_mfma_f32_32x32x16_bf16 v[0:15], v[0:3], v[4:7], 0
	v_mfma_f32_32x32x16_bf16 v[48:63], v[108:111], v[134:137], v[48:63]
	ds_read_b128 v[134:137], v125 offset:18464
	v_mfma_f32_32x32x16_bf16 v[32:47], v[108:111], v[138:141], v[32:47]
	s_waitcnt lgkmcnt(0)
	v_mfma_f32_32x32x16_bf16 v[16:31], v[108:111], v[134:137], v[16:31]
	v_mfma_f32_32x32x16_bf16 v[0:15], v[108:111], v[142:145], v[0:15]
	ds_read_b128 v[108:111], v68 offset:35904
	ds_read_b128 v[134:137], v126 offset:1088
	s_waitcnt lgkmcnt(0)
	v_mfma_f32_32x32x16_bf16 v[32:47], v[108:111], v[134:137], v[32:47]
	ds_read_b128 v[134:137], v125 offset:18496
	s_waitcnt lgkmcnt(0)
	v_mfma_f32_32x32x16_bf16 v[16:31], v[108:111], v[134:137], v[16:31]
	ds_read_b128 v[134:137], v127 offset:1088
	s_waitcnt lgkmcnt(0)
	v_mfma_f32_32x32x16_bf16 v[0:15], v[108:111], v[134:137], v[0:15]
	ds_read_b128 v[108:111], v68 offset:35936
	ds_read_b128 v[134:137], v126 offset:1120
	s_waitcnt lgkmcnt(0)
	v_mfma_f32_32x32x16_bf16 v[32:47], v[108:111], v[134:137], v[32:47]
	ds_read_b128 v[134:137], v125 offset:18528
	s_waitcnt lgkmcnt(0)
	v_mfma_f32_32x32x16_bf16 v[16:31], v[108:111], v[134:137], v[16:31]
	ds_read_b128 v[134:137], v127 offset:1120
	s_waitcnt lgkmcnt(0)
	v_mfma_f32_32x32x16_bf16 v[0:15], v[108:111], v[134:137], v[0:15]
	ds_read_b128 v[108:111], v68 offset:35968
	ds_read_b128 v[134:137], v125 offset:18560
	s_waitcnt lgkmcnt(0)
	v_mfma_f32_32x32x16_bf16 v[16:31], v[108:111], v[134:137], v[16:31]
	ds_read_b128 v[134:137], v127 offset:1152
	s_waitcnt lgkmcnt(0)
	v_mfma_f32_32x32x16_bf16 v[0:15], v[108:111], v[134:137], v[0:15]
	ds_read_b128 v[108:111], v68 offset:36000
	ds_read_b128 v[134:137], v125 offset:18592
	s_waitcnt lgkmcnt(0)
	v_mfma_f32_32x32x16_bf16 v[16:31], v[108:111], v[134:137], v[16:31]
	ds_read_b128 v[134:137], v127 offset:1184
	s_waitcnt lgkmcnt(0)
	v_mfma_f32_32x32x16_bf16 v[0:15], v[108:111], v[134:137], v[0:15]
	ds_read_b128 v[108:111], v68 offset:36032
	ds_read_b128 v[134:137], v127 offset:1216
	s_waitcnt lgkmcnt(0)
	v_mfma_f32_32x32x16_bf16 v[0:15], v[108:111], v[134:137], v[0:15]
	ds_read_b128 v[108:111], v68 offset:36064
	ds_read_b128 v[134:137], v127 offset:1248
	s_waitcnt lgkmcnt(0)
	s_barrier
	v_mfma_f32_32x32x16_bf16 v[0:15], v[108:111], v[134:137], v[0:15]
	v_or_b32_e32 v134, s78, v67
	s_lshl_b32 s78, s18, 10
	v_lshlrev_b32_e32 v134, 2, v134
	v_lshl_add_u64 v[110:111], v[106:107], 0, s[78:79]
	s_waitcnt vmcnt(0)
	v_mov_b32_e32 v152, v226
	v_mov_b64_e32 v[136:137], v[210:211]
	v_mov_b64_e32 v[138:139], v[212:213]
	v_mov_b64_e32 v[140:141], v[214:215]
	v_mov_b64_e32 v[142:143], v[216:217]
	v_mov_b64_e32 v[144:145], v[218:219]
	v_mov_b64_e32 v[146:147], v[220:221]
	v_mov_b64_e32 v[148:149], v[222:223]
	v_mov_b64_e32 v[150:151], v[224:225]
	v_lshl_add_u64 v[108:109], v[70:71], 0, vcc
	v_pk_fma_f32 v[48:49], v[48:49], v[136:137], v[152:153] op_sel_hi:[1,1,0]
	v_pk_fma_f32 v[50:51], v[50:51], v[138:139], v[152:153] op_sel_hi:[1,1,0]
	ds_write_b128 v128, v[48:51]
	v_pk_fma_f32 v[48:49], v[52:53], v[140:141], v[152:153] op_sel_hi:[1,1,0]
	v_pk_fma_f32 v[50:51], v[54:55], v[142:143], v[152:153] op_sel_hi:[1,1,0]
	ds_write_b128 v128, v[48:51] offset:32
	v_pk_fma_f32 v[48:49], v[56:57], v[144:145], v[152:153] op_sel_hi:[1,1,0]
	v_pk_fma_f32 v[50:51], v[58:59], v[146:147], v[152:153] op_sel_hi:[1,1,0]
	ds_write_b128 v128, v[48:51] offset:64
	v_pk_fma_f32 v[48:49], v[60:61], v[148:149], v[152:153] op_sel_hi:[1,1,0]
	v_pk_fma_f32 v[50:51], v[62:63], v[150:151], v[152:153] op_sel_hi:[1,1,0]
	ds_write_b128 v128, v[48:51] offset:96
	v_mov_b32_e32 v48, v227
	v_pk_fma_f32 v[32:33], v[32:33], v[136:137], v[48:49] op_sel_hi:[1,1,0]
	v_pk_fma_f32 v[34:35], v[34:35], v[138:139], v[48:49] op_sel_hi:[1,1,0]
	ds_write_b128 v129, v[32:35]
	v_pk_fma_f32 v[32:33], v[36:37], v[140:141], v[48:49] op_sel_hi:[1,1,0]
	v_pk_fma_f32 v[34:35], v[38:39], v[142:143], v[48:49] op_sel_hi:[1,1,0]
	ds_write_b128 v129, v[32:35] offset:32
	v_pk_fma_f32 v[32:33], v[40:41], v[144:145], v[48:49] op_sel_hi:[1,1,0]
	v_pk_fma_f32 v[34:35], v[42:43], v[146:147], v[48:49] op_sel_hi:[1,1,0]
	ds_write_b128 v129, v[32:35] offset:64
	v_pk_fma_f32 v[32:33], v[44:45], v[148:149], v[48:49] op_sel_hi:[1,1,0]
	v_pk_fma_f32 v[34:35], v[46:47], v[150:151], v[48:49] op_sel_hi:[1,1,0]
	ds_write_b128 v129, v[32:35] offset:96
	v_lshl_add_u64 v[32:33], s[16:17], 0, v[98:99]
	v_mad_u64_u32 v[56:57], s[2:3], v32, s19, v[108:109]
	v_mad_i32_i24 v57, v33, s19, v57
	s_waitcnt lgkmcnt(0)
	s_barrier
	global_load_dwordx4 v[32:35], v[56:57], off
	v_lshl_add_u64 v[36:37], s[16:17], 0, v[100:101]
	v_mad_u64_u32 v[58:59], s[2:3], v36, s19, v[108:109]
	v_mad_i32_i24 v59, v37, s19, v59
	global_load_dwordx4 v[36:39], v[58:59], off
	v_lshl_add_u64 v[40:41], s[16:17], 0, v[102:103]
	v_mad_u64_u32 v[60:61], s[2:3], v40, s19, v[108:109]
	v_mad_i32_i24 v61, v41, s19, v61
	global_load_dwordx4 v[40:43], v[60:61], off
	v_lshl_add_u64 v[44:45], s[16:17], 0, v[104:105]
	v_mad_u64_u32 v[62:63], s[2:3], v44, s19, v[108:109]
	v_mad_i32_i24 v63, v45, s19, v63
	global_load_dwordx4 v[44:47], v[62:63], off
	ds_read_b128 v[48:51], v130
	ds_read_b128 v[52:55], v130 offset:16
	s_or_b32 s16, s16, 64
	s_cmpk_gt_i32 s39, 0x7ff
	s_waitcnt vmcnt(3)
	v_lshlrev_b32_e32 v136, 16, v32
	v_and_b32_e32 v137, 0xffff0000, v32
	s_waitcnt lgkmcnt(1)
	v_pk_mul_f32 v[48:49], v[48:49], v[136:137]
	s_nop 0
	v_cvt_pk_bf16_f32 v32, v48, v49
	v_lshlrev_b32_e32 v48, 16, v33
	v_and_b32_e32 v49, 0xffff0000, v33
	v_pk_mul_f32 v[48:49], v[50:51], v[48:49]
	s_nop 0
	v_cvt_pk_bf16_f32 v33, v48, v49
	v_lshlrev_b32_e32 v48, 16, v34
	v_and_b32_e32 v49, 0xffff0000, v34
	s_waitcnt lgkmcnt(0)
	v_pk_mul_f32 v[48:49], v[52:53], v[48:49]
	s_waitcnt vmcnt(2)
	v_lshlrev_b32_e32 v52, 16, v36
	v_cvt_pk_bf16_f32 v34, v48, v49
	v_lshlrev_b32_e32 v48, 16, v35
	v_and_b32_e32 v49, 0xffff0000, v35
	v_pk_mul_f32 v[48:49], v[54:55], v[48:49]
	v_and_b32_e32 v53, 0xffff0000, v36
	v_cvt_pk_bf16_f32 v35, v48, v49
	global_store_dwordx4 v[56:57], v[32:35], off sc1
	ds_read_b128 v[32:35], v131
	ds_read_b128 v[48:51], v131 offset:16
	v_lshlrev_b32_e32 v36, 16, v37
	v_and_b32_e32 v37, 0xffff0000, v37
	s_waitcnt lgkmcnt(1)
	v_pk_mul_f32 v[32:33], v[32:33], v[52:53]
	v_pk_mul_f32 v[34:35], v[34:35], v[36:37]
	v_cvt_pk_bf16_f32 v32, v32, v33
	v_cvt_pk_bf16_f32 v33, v34, v35
	v_lshlrev_b32_e32 v34, 16, v38
	v_and_b32_e32 v35, 0xffff0000, v38
	v_lshlrev_b32_e32 v36, 16, v39
	v_and_b32_e32 v37, 0xffff0000, v39
	s_waitcnt lgkmcnt(0)
	v_pk_mul_f32 v[34:35], v[48:49], v[34:35]
	v_pk_mul_f32 v[36:37], v[50:51], v[36:37]
	v_cvt_pk_bf16_f32 v34, v34, v35
	v_cvt_pk_bf16_f32 v35, v36, v37
	global_store_dwordx4 v[58:59], v[32:35], off sc1
	ds_read_b128 v[32:35], v132
	ds_read_b128 v[36:39], v132 offset:16
	s_waitcnt vmcnt(3)
	v_lshlrev_b32_e32 v48, 16, v40
	v_and_b32_e32 v49, 0xffff0000, v40
	v_lshlrev_b32_e32 v40, 16, v41
	v_and_b32_e32 v41, 0xffff0000, v41
	s_waitcnt lgkmcnt(1)
	v_pk_mul_f32 v[32:33], v[32:33], v[48:49]
	v_pk_mul_f32 v[34:35], v[34:35], v[40:41]
	v_cvt_pk_bf16_f32 v32, v32, v33
	v_cvt_pk_bf16_f32 v33, v34, v35
	v_lshlrev_b32_e32 v34, 16, v42
	v_and_b32_e32 v35, 0xffff0000, v42
	s_waitcnt lgkmcnt(0)
	v_pk_mul_f32 v[34:35], v[36:37], v[34:35]
	v_lshlrev_b32_e32 v36, 16, v43
	v_and_b32_e32 v37, 0xffff0000, v43
	v_pk_mul_f32 v[36:37], v[38:39], v[36:37]
	v_cvt_pk_bf16_f32 v34, v34, v35
	v_cvt_pk_bf16_f32 v35, v36, v37
	global_store_dwordx4 v[60:61], v[32:35], off sc1
	ds_read_b128 v[32:35], v133
	ds_read_b128 v[36:39], v133 offset:16
	s_waitcnt vmcnt(3)
	v_lshlrev_b32_e32 v40, 16, v44
	v_and_b32_e32 v41, 0xffff0000, v44
	s_waitcnt lgkmcnt(1)
	v_pk_mul_f32 v[32:33], v[32:33], v[40:41]
	v_lshlrev_b32_e32 v40, 16, v45
	v_and_b32_e32 v41, 0xffff0000, v45
	v_pk_mul_f32 v[34:35], v[34:35], v[40:41]
	v_cvt_pk_bf16_f32 v32, v32, v33
	v_cvt_pk_bf16_f32 v33, v34, v35
	v_lshlrev_b32_e32 v34, 16, v46
	v_and_b32_e32 v35, 0xffff0000, v46
	s_waitcnt lgkmcnt(0)
	v_pk_mul_f32 v[34:35], v[36:37], v[34:35]
	v_lshlrev_b32_e32 v36, 16, v47
	v_and_b32_e32 v37, 0xffff0000, v47
	v_pk_mul_f32 v[36:37], v[38:39], v[36:37]
	v_cvt_pk_bf16_f32 v34, v34, v35
	v_cvt_pk_bf16_f32 v35, v36, v37
	global_store_dwordx4 v[62:63], v[32:35], off sc1
	s_barrier
	v_mov_b32_e32 v48, v228
	v_mov_b64_e32 v[32:33], v[210:211]
	v_mov_b64_e32 v[34:35], v[212:213]
	v_mov_b64_e32 v[36:37], v[214:215]
	v_mov_b64_e32 v[38:39], v[216:217]
	v_mov_b64_e32 v[40:41], v[218:219]
	v_mov_b64_e32 v[42:43], v[220:221]
	v_mov_b64_e32 v[44:45], v[222:223]
	v_mov_b64_e32 v[46:47], v[224:225]
	v_pk_fma_f32 v[16:17], v[16:17], v[32:33], v[48:49] op_sel_hi:[1,1,0]
	v_pk_fma_f32 v[18:19], v[18:19], v[34:35], v[48:49] op_sel_hi:[1,1,0]
	ds_write_b128 v128, v[16:19]
	v_pk_fma_f32 v[16:17], v[20:21], v[36:37], v[48:49] op_sel_hi:[1,1,0]
	v_pk_fma_f32 v[18:19], v[22:23], v[38:39], v[48:49] op_sel_hi:[1,1,0]
	ds_write_b128 v128, v[16:19] offset:32
	v_pk_fma_f32 v[16:17], v[24:25], v[40:41], v[48:49] op_sel_hi:[1,1,0]
	v_pk_fma_f32 v[18:19], v[26:27], v[42:43], v[48:49] op_sel_hi:[1,1,0]
	ds_write_b128 v128, v[16:19] offset:64
	v_pk_fma_f32 v[16:17], v[28:29], v[44:45], v[48:49] op_sel_hi:[1,1,0]
	v_pk_fma_f32 v[18:19], v[30:31], v[46:47], v[48:49] op_sel_hi:[1,1,0]
	ds_write_b128 v128, v[16:19] offset:96
	v_mov_b32_e32 v16, v229
	v_pk_fma_f32 v[0:1], v[0:1], v[32:33], v[16:17] op_sel_hi:[1,1,0]
	v_pk_fma_f32 v[2:3], v[2:3], v[34:35], v[16:17] op_sel_hi:[1,1,0]
	ds_write_b128 v129, v[0:3]
	v_pk_fma_f32 v[0:1], v[4:5], v[36:37], v[16:17] op_sel_hi:[1,1,0]
	v_pk_fma_f32 v[2:3], v[6:7], v[38:39], v[16:17] op_sel_hi:[1,1,0]
	ds_write_b128 v129, v[0:3] offset:32
	v_pk_fma_f32 v[0:1], v[8:9], v[40:41], v[16:17] op_sel_hi:[1,1,0]
	v_pk_fma_f32 v[2:3], v[10:11], v[42:43], v[16:17] op_sel_hi:[1,1,0]
	ds_write_b128 v129, v[0:3] offset:64
	v_pk_fma_f32 v[0:1], v[12:13], v[44:45], v[16:17] op_sel_hi:[1,1,0]
	v_pk_fma_f32 v[2:3], v[14:15], v[46:47], v[16:17] op_sel_hi:[1,1,0]
	ds_write_b128 v129, v[0:3] offset:96
	v_lshl_add_u64 v[0:1], s[16:17], 0, v[98:99]
	v_mad_u64_u32 v[24:25], s[2:3], v0, s19, v[108:109]
	v_mad_i32_i24 v25, v1, s19, v25
	s_waitcnt lgkmcnt(0)
	s_barrier
	global_load_dwordx4 v[0:3], v[24:25], off
	v_lshl_add_u64 v[4:5], s[16:17], 0, v[100:101]
	v_mad_u64_u32 v[26:27], s[2:3], v4, s19, v[108:109]
	v_mad_i32_i24 v27, v5, s19, v27
	global_load_dwordx4 v[4:7], v[26:27], off
	v_lshl_add_u64 v[8:9], s[16:17], 0, v[102:103]
	v_mad_u64_u32 v[28:29], s[2:3], v8, s19, v[108:109]
	v_mad_i32_i24 v29, v9, s19, v29
	global_load_dwordx4 v[8:11], v[28:29], off
	v_lshl_add_u64 v[12:13], s[16:17], 0, v[104:105]
	v_mad_u64_u32 v[30:31], s[2:3], v12, s19, v[108:109]
	v_mad_i32_i24 v31, v13, s19, v31
	global_load_dwordx4 v[12:15], v[30:31], off
	ds_read_b128 v[16:19], v130
	ds_read_b128 v[20:23], v130 offset:16
	s_waitcnt vmcnt(3)
	v_lshlrev_b32_e32 v32, 16, v0
	v_and_b32_e32 v33, 0xffff0000, v0
	s_waitcnt lgkmcnt(1)
	v_pk_mul_f32 v[16:17], v[16:17], v[32:33]
	s_nop 0
	v_cvt_pk_bf16_f32 v0, v16, v17
	v_lshlrev_b32_e32 v16, 16, v1
	v_and_b32_e32 v17, 0xffff0000, v1
	v_pk_mul_f32 v[16:17], v[18:19], v[16:17]
	s_nop 0
	v_cvt_pk_bf16_f32 v1, v16, v17
	v_lshlrev_b32_e32 v16, 16, v2
	v_and_b32_e32 v17, 0xffff0000, v2
	s_waitcnt lgkmcnt(0)
	v_pk_mul_f32 v[16:17], v[20:21], v[16:17]
	s_waitcnt vmcnt(2)
	v_lshlrev_b32_e32 v20, 16, v4
	v_cvt_pk_bf16_f32 v2, v16, v17
	v_lshlrev_b32_e32 v16, 16, v3
	v_and_b32_e32 v17, 0xffff0000, v3
	v_pk_mul_f32 v[16:17], v[22:23], v[16:17]
	v_and_b32_e32 v21, 0xffff0000, v4
	v_cvt_pk_bf16_f32 v3, v16, v17
	global_store_dwordx4 v[24:25], v[0:3], off sc1
	ds_read_b128 v[0:3], v131
	ds_read_b128 v[16:19], v131 offset:16
	v_lshlrev_b32_e32 v4, 16, v5
	v_and_b32_e32 v5, 0xffff0000, v5
	s_waitcnt lgkmcnt(1)
	v_pk_mul_f32 v[0:1], v[0:1], v[20:21]
	v_pk_mul_f32 v[2:3], v[2:3], v[4:5]
	v_cvt_pk_bf16_f32 v0, v0, v1
	v_cvt_pk_bf16_f32 v1, v2, v3
	v_lshlrev_b32_e32 v2, 16, v6
	v_and_b32_e32 v3, 0xffff0000, v6
	v_lshlrev_b32_e32 v4, 16, v7
	v_and_b32_e32 v5, 0xffff0000, v7
	s_waitcnt lgkmcnt(0)
	v_pk_mul_f32 v[2:3], v[16:17], v[2:3]
	v_pk_mul_f32 v[4:5], v[18:19], v[4:5]
	v_cvt_pk_bf16_f32 v2, v2, v3
	v_cvt_pk_bf16_f32 v3, v4, v5
	global_store_dwordx4 v[26:27], v[0:3], off sc1
	ds_read_b128 v[0:3], v132
	ds_read_b128 v[4:7], v132 offset:16
	s_waitcnt vmcnt(3)
	v_lshlrev_b32_e32 v16, 16, v8
	v_and_b32_e32 v17, 0xffff0000, v8
	v_lshlrev_b32_e32 v8, 16, v9
	v_and_b32_e32 v9, 0xffff0000, v9
	s_waitcnt lgkmcnt(1)
	v_pk_mul_f32 v[0:1], v[0:1], v[16:17]
	v_pk_mul_f32 v[2:3], v[2:3], v[8:9]
	v_cvt_pk_bf16_f32 v0, v0, v1
	v_cvt_pk_bf16_f32 v1, v2, v3
	v_lshlrev_b32_e32 v2, 16, v10
	v_and_b32_e32 v3, 0xffff0000, v10
	s_waitcnt lgkmcnt(0)
	v_pk_mul_f32 v[2:3], v[4:5], v[2:3]
	v_lshlrev_b32_e32 v4, 16, v11
	v_and_b32_e32 v5, 0xffff0000, v11
	v_pk_mul_f32 v[4:5], v[6:7], v[4:5]
	v_cvt_pk_bf16_f32 v2, v2, v3
	v_cvt_pk_bf16_f32 v3, v4, v5
	global_store_dwordx4 v[28:29], v[0:3], off sc1
	ds_read_b128 v[0:3], v133
	ds_read_b128 v[4:7], v133 offset:16
	s_waitcnt vmcnt(3)
	v_lshlrev_b32_e32 v8, 16, v12
	v_and_b32_e32 v9, 0xffff0000, v12
	s_waitcnt lgkmcnt(1)
	v_pk_mul_f32 v[0:1], v[0:1], v[8:9]
	v_lshlrev_b32_e32 v8, 16, v13
	v_and_b32_e32 v9, 0xffff0000, v13
	v_pk_mul_f32 v[2:3], v[2:3], v[8:9]
	v_cvt_pk_bf16_f32 v0, v0, v1
	v_cvt_pk_bf16_f32 v1, v2, v3
	v_lshlrev_b32_e32 v2, 16, v14
	v_and_b32_e32 v3, 0xffff0000, v14
	s_waitcnt lgkmcnt(0)
	v_pk_mul_f32 v[2:3], v[4:5], v[2:3]
	v_lshlrev_b32_e32 v4, 16, v15
	v_and_b32_e32 v5, 0xffff0000, v15
	v_pk_mul_f32 v[4:5], v[6:7], v[4:5]
	v_cvt_pk_bf16_f32 v2, v2, v3
	v_cvt_pk_bf16_f32 v3, v4, v5
	global_store_dwordx4 v[30:31], v[0:3], off sc1
	s_barrier
	s_cbranch_scc1 .LBB0_212
